# SWA head loop: waves 4-7 sleep 16x64 cycles once per unit after the staging barrier so the two waves of a SIMD stop running their MFMA bursts and softmax VALU stretches in lockstep
# speedup vs baseline: 1.0036x; 1.0011x over previous
.LBB0_426:
	v_cndmask_b32_e64 v3, 0, 1, s[92:93]
	v_mov_b64_e32 v[0:1], s[10:11]
	v_readfirstlane_b32 s12, v3
	s_lshl_b32 s9, s12, 2
	s_or_b32 s9, s9, 2
	s_lshl_b32 s12, s12, 9
	s_add_u32 s12, s86, s12
	s_addc_u32 s13, s87, 0
	s_ashr_i32 s26, s8, 7
	s_bfe_u32 s24, s8, 0x60001
	s_ashr_i32 s27, s26, 31
	s_lshl_b64 s[28:29], s[26:27], 13
	s_lshl_b32 s14, s24, 7
	s_or_b32 s28, s28, s14
	s_lshl_b32 s25, s26, 13
	v_lshl_add_u64 v[126:127], s[28:29], 0, v[114:115]
	s_or_b32 s14, s25, s14
	v_or_b32_e32 v4, v126, v112
	s_addk_i32 s14, 0xff80
	s_and_b32 s15, s8, 1
	v_mad_u64_u32 v[4:5], s[28:29], v4, s62, v[0:1]
	v_add_u32_e32 v6, s14, v136
	v_mad_i32_i24 v5, v127, s62, v5
	s_lshl_b32 s94, s15, 9
	v_max_i32_e32 v6, s25, v6
	v_lshl_add_u64 v[4:5], v[4:5], 0, s[94:95]
	v_mad_i64_i32 v[6:7], s[26:27], v6, s62, v[0:1]
	s_lshl_b32 s94, s15, 7
	v_lshl_add_u64 v[6:7], v[6:7], 0, s[94:95]
	v_mov_b32_e32 v123, v2
	v_lshl_add_u64 v[6:7], v[6:7], 0, v[122:123]
	s_mov_b64 s[26:27], 0x1000
	v_lshl_add_u64 v[8:9], v[6:7], 0, s[26:27]
	global_load_dwordx4 v[12:15], v[8:9], off offset:16
	global_load_dwordx4 v[16:19], v[8:9], off offset:32
	s_movk_i32 s28, 0x1000
	v_add_co_u32_e32 v6, vcc, s28, v6
	v_mov_b32_e32 v121, v2
	s_nop 0
	v_addc_co_u32_e32 v7, vcc, 0, v7, vcc
	global_load_dwordx4 v[20:23], v[6:7], off
	global_load_dwordx4 v[24:27], v[116:117], off offset:16
	global_load_dwordx4 v[28:31], v[116:117], off
	global_load_dwordx4 v[32:35], v[8:9], off offset:48
	v_add_u32_e32 v6, s14, v137
	v_max_i32_e32 v10, s25, v6
	v_mad_i64_i32 v[6:7], s[26:27], v10, s62, v[0:1]
	v_mov_b32_e32 v125, v2
	v_or_b32_e32 v10, 1, v10
	v_lshl_add_u64 v[4:5], v[4:5], 0, v[120:121]
	v_lshl_add_u64 v[6:7], v[6:7], 0, s[94:95]
	v_mad_i64_i32 v[0:1], s[26:27], v10, s62, v[0:1]
	global_load_dwordx4 v[96:99], v[4:5], off offset:3072
	global_load_dwordx4 v[100:103], v[4:5], off offset:3136
	v_lshl_add_u64 v[4:5], v[6:7], 0, v[124:125]
	s_mov_b64 s[16:17], 0x1100
	v_lshl_add_u64 v[0:1], v[0:1], 0, s[94:95]
	v_lshl_add_u64 v[48:49], v[4:5], 0, s[16:17]
	v_add_co_u32_e32 v4, vcc, s28, v4
	v_lshl_add_u64 v[0:1], v[0:1], 0, v[124:125]
	s_nop 0
	v_addc_co_u32_e32 v5, vcc, 0, v5, vcc
	v_lshl_add_u64 v[50:51], v[0:1], 0, s[16:17]
	v_add_co_u32_e32 v0, vcc, s28, v0
	s_mov_b32 s14, 0xffff0000
	s_nop 0
	v_addc_co_u32_e32 v1, vcc, 0, v1, vcc
	global_load_dwordx4 v[4:7], v[4:5], off offset:256
	s_nop 0
	global_load_dwordx4 v[8:11], v[0:1], off offset:256
	v_readlane_b32 s16, v253, 11
	v_readlane_b32 s17, v253, 12
	v_mov_b32_e32 v129, v2
	s_mov_b64 s[70:71], 0
	s_movk_i32 s94, 0x220
	s_mov_b32 s18, 0x41800000
	s_mov_b32 s19, 0x41880000
	s_mov_b32 s20, 0x41900000
	s_mov_b32 s21, 0x41980000
	s_mov_b32 s22, 0x42000000
	s_waitcnt vmcnt(9)
	v_and_b32_e32 v53, 0xffff0000, v13
	v_and_b32_e32 v52, 0xffff0000, v12
	v_and_b32_e32 v57, 0xffff0000, v15
	v_and_b32_e32 v56, 0xffff0000, v14
	v_lshlrev_b32_e32 v1, 16, v13
	v_lshlrev_b32_e32 v0, 16, v12
	v_lshlrev_b32_e32 v55, 16, v15
	v_lshlrev_b32_e32 v54, 16, v14
	s_waitcnt vmcnt(8)
	v_and_b32_e32 v59, 0xffff0000, v16
	v_and_b32_e32 v61, 0xffff0000, v17
	v_pk_mul_f32 v[12:13], v[52:53], v[52:53]
	v_pk_mul_f32 v[14:15], v[56:57], v[56:57]
	v_lshlrev_b32_e32 v58, 16, v16
	v_lshlrev_b32_e32 v60, 16, v17
	v_lshlrev_b32_e32 v62, 16, v18
	v_and_b32_e32 v63, 0xffff0000, v18
	v_mul_f32_e32 v16, v59, v59
	v_mul_f32_e32 v18, v61, v61
	v_pk_fma_f32 v[12:13], v[0:1], v[0:1], v[12:13]
	v_pk_fma_f32 v[14:15], v[54:55], v[54:55], v[14:15]
	v_lshlrev_b32_e32 v64, 16, v19
	v_and_b32_e32 v65, 0xffff0000, v19
	v_pk_fma_f32 v[66:67], v[58:59], v[58:59], v[16:17] op_sel_hi:[1,1,0]
	v_pk_fma_f32 v[68:69], v[60:61], v[60:61], v[18:19] op_sel_hi:[1,1,0]
	v_pk_add_f32 v[72:73], v[12:13], v[12:13] op_sel:[0,1] op_sel_hi:[1,0]
	v_pk_add_f32 v[74:75], v[14:15], v[14:15] op_sel:[0,1] op_sel_hi:[1,0]
	global_load_dwordx4 v[12:15], v[116:117], off offset:48
	global_load_dwordx4 v[16:19], v[116:117], off offset:32
	v_mul_f32_e32 v36, v63, v63
	s_waitcnt vmcnt(9)
	v_and_b32_e32 v79, 0xffff0000, v23
	v_and_b32_e32 v81, 0xffff0000, v22
	v_pk_fma_f32 v[70:71], v[62:63], v[62:63], v[36:37] op_sel_hi:[1,1,0]
	v_lshlrev_b32_e32 v78, 16, v23
	v_lshlrev_b32_e32 v80, 16, v22
	v_mov_b32_e32 v36, v81
	v_mov_b32_e32 v37, v79
	v_mov_b32_e32 v22, v80
	v_mov_b32_e32 v23, v78
	v_pk_mul_f32 v[36:37], v[36:37], v[36:37]
	v_mul_f32_e32 v38, v65, v65
	v_pk_fma_f32 v[22:23], v[22:23], v[22:23], v[36:37]
	v_pk_fma_f32 v[76:77], v[64:65], v[64:65], v[38:39] op_sel_hi:[1,1,0]
	v_pk_add_f32 v[82:83], v[22:23], v[22:23] op_sel:[0,1] op_sel_hi:[1,0]
	v_lshlrev_b32_e32 v84, 16, v21
	v_and_b32_e32 v85, 0xffff0000, v21
	v_lshlrev_b32_e32 v86, 16, v20
	v_and_b32_e32 v87, 0xffff0000, v20
	global_load_dwordx4 v[20:23], v[116:117], off offset:80
	global_load_dwordx4 v[36:39], v[116:117], off offset:64
	v_mov_b32_e32 v42, v87
	v_mov_b32_e32 v43, v85
	v_mov_b32_e32 v40, v86
	v_mov_b32_e32 v41, v84
	v_pk_mul_f32 v[42:43], v[42:43], v[42:43]
	s_waitcnt vmcnt(8)
	v_lshlrev_b32_e32 v90, 16, v35
	v_pk_fma_f32 v[40:41], v[40:41], v[40:41], v[42:43]
	v_and_b32_e32 v91, 0xffff0000, v35
	v_pk_add_f32 v[88:89], v[40:41], v[40:41] op_sel:[0,1] op_sel_hi:[1,0]
	global_load_dwordx4 v[40:43], v[116:117], off offset:112
	global_load_dwordx4 v[44:47], v[116:117], off offset:96
	v_pk_mul_f32 v[92:93], v[90:91], v[90:91]
	s_nop 0
	v_mov_b32_e32 v71, v92
	v_mov_b32_e32 v77, v93
	v_pk_add_f32 v[70:71], v[70:71], v[76:77]
	v_lshlrev_b32_e32 v76, 16, v34
	v_and_b32_e32 v77, 0xffff0000, v34
	v_pk_mul_f32 v[34:35], v[76:77], v[76:77]
	s_nop 0
	v_mov_b32_e32 v67, v34
	v_mov_b32_e32 v69, v35
	v_pk_add_f32 v[34:35], v[66:67], v[68:69]
	v_lshlrev_b32_e32 v66, 16, v33
	v_pk_add_f32 v[34:35], v[34:35], v[70:71]
	v_and_b32_e32 v67, 0xffff0000, v33
	v_lshlrev_b32_e32 v70, 16, v32
	v_and_b32_e32 v71, 0xffff0000, v32
	v_pk_mul_f32 v[68:69], v[66:67], v[66:67]
	v_pk_mul_f32 v[32:33], v[70:71], v[70:71]
	v_mov_b32_e32 v73, v68
	v_mov_b32_e32 v75, v69
	v_mov_b32_e32 v89, v32
	v_mov_b32_e32 v83, v33
	v_pk_add_f32 v[68:69], v[72:73], v[74:75]
	v_pk_add_f32 v[32:33], v[88:89], v[82:83]
	s_nop 0
	v_pk_add_f32 v[32:33], v[32:33], v[68:69]
	v_mov_b32_e32 v68, v0
	v_pk_add_f32 v[32:33], v[32:33], v[34:35]
	v_mov_b32_e32 v69, v52
	v_add_f32_e32 v72, v32, v33
	global_load_dwordx4 v[32:35], v[48:49], off offset:16
	s_nop 0
	global_load_dwordx4 v[48:51], v[50:51], off offset:16
	ds_bpermute_b32 v73, v138, v72
	v_mov_b32_e32 v52, v1
	s_waitcnt lgkmcnt(0)
	v_add_f32_e32 v0, v72, v73
	v_fmamk_f32 v0, v0, 0x3c800000, v209
	v_mul_f32_e32 v1, 0x4b800000, v0
	v_cmp_gt_f32_e32 vcc, s68, v0
	s_nop 1
	v_cndmask_b32_e32 v0, v0, v1, vcc
	v_rsq_f32_e32 v72, v0
	v_mov_b32_e32 v0, v54
	v_mov_b32_e32 v1, v56
	v_mov_b32_e32 v56, v55
	v_mul_f32_e32 v54, 0x45800000, v72
	v_cndmask_b32_e32 v54, v72, v54, vcc
	v_pk_mul_f32 v[72:73], v[54:55], v[86:87] op_sel_hi:[0,1]
	v_pk_mul_f32 v[28:29], v[28:29], v[72:73]
	v_pk_mul_f32 v[72:73], v[54:55], v[84:85] op_sel_hi:[0,1]
	v_pk_mul_f32 v[30:31], v[30:31], v[72:73]
	v_cvt_pk_bf16_f32 v28, v28, v29
	v_cvt_pk_bf16_f32 v29, v30, v31
	v_pk_mul_f32 v[30:31], v[54:55], v[80:81] op_sel_hi:[0,1]
	v_pk_mul_f32 v[24:25], v[24:25], v[30:31]
	v_pk_mul_f32 v[0:1], v[54:55], v[0:1] op_sel_hi:[0,1]
	v_cvt_pk_bf16_f32 v30, v24, v25
	v_pk_mul_f32 v[24:25], v[54:55], v[78:79] op_sel_hi:[0,1]
	v_pk_mul_f32 v[24:25], v[26:27], v[24:25]
	s_waitcnt vmcnt(7)
	v_pk_mul_f32 v[0:1], v[12:13], v[0:1]
	v_cvt_pk_bf16_f32 v31, v24, v25
	v_pk_mul_f32 v[24:25], v[54:55], v[68:69] op_sel_hi:[0,1]
	s_waitcnt vmcnt(6)
	v_pk_mul_f32 v[16:17], v[16:17], v[24:25]
	v_pk_mul_f32 v[24:25], v[54:55], v[52:53] op_sel_hi:[0,1]
	v_pk_mul_f32 v[18:19], v[18:19], v[24:25]
	v_cvt_pk_bf16_f32 v16, v16, v17
	v_cvt_pk_bf16_f32 v17, v18, v19
	v_cvt_pk_bf16_f32 v18, v0, v1
	v_pk_mul_f32 v[0:1], v[54:55], v[56:57] op_sel_hi:[0,1]
	v_pk_mul_f32 v[0:1], v[14:15], v[0:1]
	ds_write_b128 v139, v[28:31]
	v_cvt_pk_bf16_f32 v19, v0, v1
	v_pk_mul_f32 v[0:1], v[54:55], v[58:59] op_sel_hi:[0,1]
	s_waitcnt vmcnt(4)
	v_pk_mul_f32 v[0:1], v[36:37], v[0:1]
	ds_write_b128 v139, v[16:19] offset:16
	v_cvt_pk_bf16_f32 v12, v0, v1
	v_pk_mul_f32 v[0:1], v[54:55], v[60:61] op_sel_hi:[0,1]
	v_pk_mul_f32 v[0:1], v[38:39], v[0:1]
	s_nop 0
	v_cvt_pk_bf16_f32 v13, v0, v1
	v_pk_mul_f32 v[0:1], v[54:55], v[62:63] op_sel_hi:[0,1]
	v_pk_mul_f32 v[0:1], v[20:21], v[0:1]
	s_nop 0
	v_cvt_pk_bf16_f32 v14, v0, v1
	v_pk_mul_f32 v[0:1], v[54:55], v[64:65] op_sel_hi:[0,1]
	v_pk_mul_f32 v[0:1], v[22:23], v[0:1]
	s_nop 0
	v_cvt_pk_bf16_f32 v15, v0, v1
	v_pk_mul_f32 v[0:1], v[54:55], v[70:71] op_sel_hi:[0,1]
	s_waitcnt vmcnt(2)
	v_pk_mul_f32 v[0:1], v[44:45], v[0:1]
	ds_write_b128 v139, v[12:15] offset:32
	v_cvt_pk_bf16_f32 v12, v0, v1
	v_pk_mul_f32 v[0:1], v[54:55], v[66:67] op_sel_hi:[0,1]
	v_pk_mul_f32 v[0:1], v[46:47], v[0:1]
	s_nop 0
	v_cvt_pk_bf16_f32 v13, v0, v1
	v_pk_mul_f32 v[0:1], v[54:55], v[76:77] op_sel_hi:[0,1]
	v_pk_mul_f32 v[0:1], v[40:41], v[0:1]
	s_nop 0
	v_cvt_pk_bf16_f32 v14, v0, v1
	v_pk_mul_f32 v[0:1], v[54:55], v[90:91] op_sel_hi:[0,1]
	v_pk_mul_f32 v[0:1], v[42:43], v[0:1]
	s_nop 0
	v_cvt_pk_bf16_f32 v15, v0, v1
	v_and_b32_e32 v0, 0xffff, v4
	v_lshrrev_b32_e32 v1, 16, v4
	v_lshl_or_b32 v0, v8, 16, v0
	v_and_or_b32 v1, v8, s14, v1
	v_and_b32_e32 v28, 1, v208
	v_lshlrev_b32_e32 v28, 4, v28
	v_xor_b32_e32 v28, v145, v28
	v_xor_b32_e32 v29, 8, v28
	v_add_u32_e32 v4, 0x9000, v28
	ds_write_b128 v139, v[12:15] offset:48
	ds_write2_b32 v4, v0, v1 offset1:136
	v_and_b32_e32 v0, 0xffff, v5
	v_lshrrev_b32_e32 v1, 16, v5
	v_lshl_or_b32 v0, v9, 16, v0
	v_and_or_b32 v1, v9, s14, v1
	v_add_u32_e32 v4, 0x9400, v28
	ds_write2_b32 v4, v0, v1 offset0:16 offset1:152
	v_and_b32_e32 v0, 0xffff, v6
	v_lshrrev_b32_e32 v1, 16, v6
	v_lshl_or_b32 v0, v10, 16, v0
	v_and_or_b32 v1, v10, s14, v1
	v_add_u32_e32 v4, 0x9800, v28
	ds_write2_b32 v4, v0, v1 offset0:32 offset1:168
	v_and_b32_e32 v0, 0xffff, v7
	v_lshrrev_b32_e32 v1, 16, v7
	v_lshl_or_b32 v0, v11, 16, v0
	v_and_or_b32 v1, v11, s14, v1
	v_add_u32_e32 v4, 0x9c00, v28
	ds_write2_b32 v4, v0, v1 offset0:48 offset1:184
	s_waitcnt vmcnt(1)
	v_and_b32_e32 v0, 0xffff, v32
	v_lshrrev_b32_e32 v1, 16, v32
	s_waitcnt vmcnt(0)
	v_lshl_or_b32 v0, v48, 16, v0
	v_and_or_b32 v1, v48, s14, v1
	v_add_u32_e32 v4, 0xa000, v29
	ds_write2_b32 v4, v0, v1 offset0:64 offset1:200
	v_and_b32_e32 v0, 0xffff, v33
	v_lshrrev_b32_e32 v1, 16, v33
	v_lshl_or_b32 v0, v49, 16, v0
	v_and_or_b32 v1, v49, s14, v1
	v_add_u32_e32 v4, 0xa400, v29
	ds_write2_b32 v4, v0, v1 offset0:80 offset1:216
	v_and_b32_e32 v0, 0xffff, v34
	v_lshrrev_b32_e32 v1, 16, v34
	v_lshl_or_b32 v0, v50, 16, v0
	v_and_or_b32 v1, v50, s14, v1
	v_add_u32_e32 v4, 0xa800, v29
	ds_write2_b32 v4, v0, v1 offset0:96 offset1:232
	v_and_b32_e32 v0, 0xffff, v35
	v_lshrrev_b32_e32 v1, 16, v35
	v_lshl_or_b32 v0, v51, 16, v0
	v_and_or_b32 v1, v51, s14, v1
	v_add_u32_e32 v4, 0xac00, v29
	ds_write2_b32 v4, v0, v1 offset0:112 offset1:248
	s_waitcnt lgkmcnt(0)
	s_barrier
	v_readfirstlane_b32 s32, v208
	s_cmp_lt_u32 s32, 0x100
	s_cbranch_scc1 .Lswa_stag
	s_sleep 16
.Lswa_stag:
	global_load_dwordx4 v[4:7], v[118:119], off
	global_load_dwordx4 v[8:11], v[118:119], off offset:16
	global_load_dwordx4 v[12:15], v[118:119], off offset:128
	global_load_dwordx4 v[16:19], v[118:119], off offset:144
	s_lshl_b32 s14, s15, 4
	v_mov_b32_e32 v0, s14
	global_load_dwordx4 v[20:23], v0, s[6:7]
	v_lshlrev_b32_e32 v0, 8, v3
	v_or_b32_e32 v128, 64, v0
	v_add_u32_e32 v0, v140, v144
	ds_read_b128 v[24:27], v0
	ds_read_b128 v[28:31], v0 offset:64
	ds_read_b128 v[32:35], v146
	ds_read_b128 v[36:39], v146 offset:64
	ds_read_b128 v[40:43], v147
	ds_read_b128 v[44:47], v147 offset:64
	ds_read_b128 v[48:51], v148
	ds_read_b128 v[52:55], v148 offset:64
	ds_read_b128 v[56:59], v149
	ds_read_b128 v[60:63], v149 offset:64
	ds_read_b128 v[64:67], v150
	ds_read_b128 v[68:71], v150 offset:64
	ds_read_b128 v[72:75], v151
	ds_read_b128 v[76:79], v151 offset:64
	ds_read_b128 v[80:83], v152
	ds_read_b128 v[84:87], v152 offset:64
	ds_read_b128 v[88:91], v153
	ds_read_b128 v[92:95], v153 offset:64
	s_lshl_b32 s15, s15, 2
	s_cmp_lg_u32 s24, 0
	s_cselect_b64 s[40:41], -1, 0
	s_or_b64 s[78:79], s[40:41], s[16:17]
	v_readlane_b32 s16, v253, 13
	v_readlane_b32 s17, v253, 14
	s_or_b64 s[24:25], s[40:41], s[16:17]
	v_readlane_b32 s16, v253, 15
	v_readlane_b32 s17, v253, 16
	s_or_b64 s[26:27], s[40:41], s[16:17]
	v_readlane_b32 s16, v253, 17
	v_readlane_b32 s17, v253, 18
	s_or_b64 s[28:29], s[40:41], s[16:17]
	v_readlane_b32 s16, v253, 19
	v_readlane_b32 s17, v253, 20
	s_or_b64 s[30:31], s[40:41], s[16:17]
	v_readlane_b32 s16, v253, 21
	v_readlane_b32 s17, v253, 22
	s_or_b64 s[34:35], s[40:41], s[16:17]
	v_readlane_b32 s16, v253, 23
	v_readlane_b32 s17, v253, 24
	s_or_b64 s[36:37], s[40:41], s[16:17]
	v_readlane_b32 s16, v253, 25
	v_readlane_b32 s17, v253, 26
	s_or_b64 s[38:39], s[40:41], s[16:17]
	v_readlane_b32 s16, v253, 27
	v_readlane_b32 s17, v253, 28
	s_mov_b32 s14, 0
	s_or_b64 s[84:85], s[40:41], s[16:17]
	s_mov_b32 s16, 0x42800000
	s_mov_b32 s17, 0x40400000
	s_branch .LBB0_429
